# MLA attention: next tile's K/V register loads issued between the two 32-key sub-blocks instead of as a burst right after the staging barrier
# baseline (speedup 1.0000x reference)
.LBB0_681:
	s_add_i32 s6, s6, 1
	s_cmp_ge_u32 s6, s19
	s_waitcnt lgkmcnt(0)
	s_barrier
	s_waitcnt vmcnt(9)
	ds_write_b128 v205, v[136:139]
	s_waitcnt vmcnt(8)
	ds_write_b128 v205, v[144:147] offset:6400
	s_waitcnt vmcnt(7)
	ds_write_b128 v205, v[152:155] offset:12800
	s_waitcnt vmcnt(6)
	ds_write_b128 v205, v[156:159] offset:19200
	s_waitcnt vmcnt(5)
	ds_write_b128 v206, v[160:163] offset:256
	s_waitcnt vmcnt(3)
	ds_write_b128 v206, v[168:171] offset:13056
	ds_write_b128 v207, v[164:167] offset:25600
	s_waitcnt vmcnt(2)
	ds_write_b128 v207, v[172:175] offset:30208
	s_waitcnt vmcnt(1)
	ds_write_b128 v207, v[176:179] offset:34816
	s_waitcnt vmcnt(0)
	ds_write_b128 v207, v[180:183] offset:39424
	s_waitcnt lgkmcnt(0)
	s_barrier
.LBB0_683:
	s_mov_b32 s38, 0
	s_mov_b64 s[28:29], -1
	s_branch .LBB0_685
.LBB0_684:
	v_pk_fma_f32 v[2:3], v[80:81], s[8:9], v[198:199] op_sel_hi:[1,0,0] neg_lo:[0,0,1] neg_hi:[0,0,1]
	v_lshl_add_u32 v0, s38, 6, v211
	v_exp_f32_e32 v14, v2
	v_exp_f32_e32 v15, v3
	v_pk_fma_f32 v[2:3], v[82:83], s[8:9], v[198:199] op_sel_hi:[1,0,0] neg_lo:[0,0,1] neg_hi:[0,0,1]
	v_pk_fma_f32 v[6:7], v[86:87], s[8:9], v[198:199] op_sel_hi:[1,0,0] neg_lo:[0,0,1] neg_hi:[0,0,1]
	v_exp_f32_e32 v216, v2
	v_exp_f32_e32 v217, v3
	v_pk_fma_f32 v[2:3], v[84:85], s[8:9], v[198:199] op_sel_hi:[1,0,0] neg_lo:[0,0,1] neg_hi:[0,0,1]
	v_exp_f32_e32 v220, v6
	v_exp_f32_e32 v218, v2
	v_exp_f32_e32 v219, v3
	ds_read_b128 v[2:5], v0 offset:25600
	ds_read_b128 v[10:13], v0 offset:25632
	v_exp_f32_e32 v221, v7
	v_cvt_pk_bf16_f32 v6, v14, v15
	v_cvt_pk_bf16_f32 v7, v216, v217
	v_cvt_pk_bf16_f32 v8, v218, v219
	v_cvt_pk_bf16_f32 v9, v220, v221
	v_pk_fma_f32 v[84:85], v[88:89], s[8:9], v[198:199] op_sel_hi:[1,0,0] neg_lo:[0,0,1] neg_hi:[0,0,1]
	s_xor_b64 s[40:41], s[28:29], -1
	s_waitcnt lgkmcnt(1)
	v_mfma_f32_32x32x16_bf16 v[64:79], v[2:5], v[6:9], v[64:79]
	ds_read_b128 v[2:5], v0 offset:30208
	ds_read_b128 v[80:83], v0 offset:30240
	v_exp_f32_e32 v88, v84
	v_exp_f32_e32 v89, v85
	s_mov_b32 s38, 1
	s_mov_b64 s[28:29], 0
	s_and_b64 vcc, exec, s[40:41]
	s_waitcnt lgkmcnt(1)
	v_mfma_f32_32x32x16_bf16 v[48:63], v[2:5], v[6:9], v[48:63]
	ds_read_b128 v[2:5], v0 offset:34816
	ds_read_b128 v[84:87], v0 offset:39424
	ds_read_b128 v[212:215], v0 offset:34848
	s_waitcnt lgkmcnt(2)
	v_mfma_f32_32x32x16_bf16 v[32:47], v[2:5], v[6:9], v[32:47]
	v_fma_f32 v2, v90, s8, -v198
	v_fma_f32 v3, v91, s8, -v198
	v_exp_f32_e32 v90, v2
	v_exp_f32_e32 v91, v3
	v_pk_fma_f32 v[2:3], v[92:93], s[8:9], v[198:199] op_sel_hi:[1,0,0] neg_lo:[0,0,1] neg_hi:[0,0,1]
	s_nop 0
	v_exp_f32_e32 v92, v2
	v_exp_f32_e32 v93, v3
	ds_read_b128 v[2:5], v0 offset:39456
	s_waitcnt lgkmcnt(2)
	v_mfma_f32_32x32x16_bf16 v[16:31], v[84:87], v[6:9], v[16:31]
	v_fma_f32 v6, v94, s8, -v198
	v_fma_f32 v7, v95, s8, -v198
	v_cvt_pk_bf16_f32 v8, v92, v93
	v_exp_f32_e32 v84, v6
	v_exp_f32_e32 v85, v7
	v_cvt_pk_bf16_f32 v6, v88, v89
	v_cvt_pk_bf16_f32 v7, v90, v91
	v_cvt_pk_bf16_f32 v9, v84, v85
	s_nop 1
	v_mfma_f32_32x32x16_bf16 v[64:79], v[10:13], v[6:9], v[64:79]
	v_add_f32_e64 v10, v14, 0
	v_add_f32_e64 v11, v15, 0
	v_add_f32_e64 v10, v216, v10
	v_add_f32_e64 v11, v217, v11
	v_add_f32_e64 v10, v218, v10
	v_add_f32_e64 v11, v219, v11
	v_pk_add_f32 v[10:11], v[220:221], v[10:11]
	v_mfma_f32_32x32x16_bf16 v[48:63], v[80:83], v[6:9], v[48:63]
	v_add_f32_e64 v10, v88, v10
	v_add_f32_e64 v11, v89, v11
	v_add_f32_e64 v10, v90, v10
	v_add_f32_e64 v11, v91, v11
	v_add_f32_e64 v10, v92, v10
	v_add_f32_e64 v11, v93, v11
	v_pk_add_f32 v[10:11], v[84:85], v[10:11]
	s_waitcnt lgkmcnt(1)
	v_mfma_f32_32x32x16_bf16 v[32:47], v[212:215], v[6:9], v[32:47]
	v_add_f32_e32 v0, v10, v11
	v_add_f32_e32 v193, v193, v0
	s_waitcnt lgkmcnt(0)
	v_mfma_f32_32x32x16_bf16 v[16:31], v[2:5], v[6:9], v[16:31]
	s_cbranch_vccnz .LBB0_680
	s_cmp_ge_u32 s6, s19
	s_cbranch_scc1 .Lmla_noload
	s_mul_i32 s98, s6, 0x30000
	s_mul_hi_u32 s99, s6, 0x30000
	s_add_u32 s98, s20, s98
	s_addc_u32 s99, s21, s99
	v_lshl_add_u64 v[2:3], s[98:99], 0, v[184:185]
	v_add_co_u32_e32 v4, vcc, 0xc000, v2
	s_nop 1
	v_addc_co_u32_e32 v5, vcc, 0, v3, vcc
	global_load_dwordx4 v[136:139], v[2:3], off
	global_load_dwordx4 v[144:147], v[4:5], off
	v_add_co_u32_e32 v4, vcc, 0x18000, v2
	s_nop 1
	v_addc_co_u32_e32 v5, vcc, 0, v3, vcc
	v_add_co_u32_e32 v2, vcc, 0x24000, v2
	s_nop 1
	v_addc_co_u32_e32 v3, vcc, 0, v3, vcc
	global_load_dwordx4 v[152:155], v[4:5], off
	global_load_dwordx4 v[156:159], v[2:3], off
	v_lshl_add_u64 v[2:3], s[98:99], 0, v[186:187]
	v_add_co_u32_e32 v4, vcc, 0x18000, v2
	s_lshl_b64 s[98:99], s[6:7], 7
	s_nop 0
	v_addc_co_u32_e32 v5, vcc, 0, v3, vcc
	global_load_dwordx4 v[160:163], v[2:3], off offset:256
	global_load_dwordx4 v[168:171], v[4:5], off offset:256
	v_lshl_add_u64 v[2:3], v[196:197], 0, s[98:99]
	v_lshl_add_u64 v[4:5], v[2:3], 0, s[22:23]
	global_load_dwordx4 v[164:167], v[2:3], off
	global_load_dwordx4 v[172:175], v[4:5], off
	v_lshl_add_u64 v[4:5], v[2:3], 0, s[24:25]
	v_lshl_add_u64 v[2:3], v[2:3], 0, s[26:27]
	global_load_dwordx4 v[176:179], v[4:5], off
	global_load_dwordx4 v[180:183], v[2:3], off
.Lmla_noload:
.LBB0_685:
	v_lshl_or_b32 v0, s38, 5, v202
	v_mad_u32_u24 v0, v0, s30, v208
	ds_read_b128 v[2:5], v0
	ds_read_b128 v[6:9], v0 offset:32
	s_waitcnt lgkmcnt(1)
	v_mfma_f32_32x32x16_bf16 v[80:95], v[2:5], v[148:151], 0
	s_waitcnt lgkmcnt(0)
	v_mfma_f32_32x32x16_bf16 v[80:95], v[6:9], v[96:99], v[80:95]
	ds_read_b128 v[2:5], v0 offset:64
	ds_read_b128 v[6:9], v0 offset:96
	s_waitcnt lgkmcnt(1)
	v_mfma_f32_32x32x16_bf16 v[80:95], v[2:5], v[100:103], v[80:95]
	s_waitcnt lgkmcnt(0)
	v_mfma_f32_32x32x16_bf16 v[80:95], v[6:9], v[104:107], v[80:95]
	ds_read_b128 v[2:5], v0 offset:128
	ds_read_b128 v[6:9], v0 offset:160
	s_waitcnt lgkmcnt(1)
	v_mfma_f32_32x32x16_bf16 v[80:95], v[2:5], v[108:111], v[80:95]
	s_waitcnt lgkmcnt(0)
	v_mfma_f32_32x32x16_bf16 v[80:95], v[6:9], v[112:115], v[80:95]
	ds_read_b128 v[2:5], v0 offset:192
	ds_read_b128 v[6:9], v0 offset:224
	s_waitcnt lgkmcnt(1)
	v_mfma_f32_32x32x16_bf16 v[80:95], v[2:5], v[116:119], v[80:95]
	s_waitcnt lgkmcnt(0)
	v_mfma_f32_32x32x16_bf16 v[80:95], v[6:9], v[120:123], v[80:95]
	ds_read_b128 v[2:5], v0 offset:256
	ds_read_b128 v[6:9], v0 offset:288
	s_waitcnt lgkmcnt(1)
	v_mfma_f32_32x32x16_bf16 v[80:95], v[2:5], v[124:127], v[80:95]
	s_waitcnt lgkmcnt(0)
	v_mfma_f32_32x32x16_bf16 v[80:95], v[6:9], v[128:131], v[80:95]
	ds_read_b128 v[2:5], v0 offset:320
	ds_read_b128 v[6:9], v0 offset:352
	s_waitcnt lgkmcnt(1)
	v_mfma_f32_32x32x16_bf16 v[80:95], v[2:5], v[132:135], v[80:95]
	s_waitcnt lgkmcnt(0)
	v_mfma_f32_32x32x16_bf16 v[80:95], v[6:9], v[140:143], v[80:95]
	s_nop 11
	v_max_f32_e32 v0, v81, v81
	v_max_f32_e32 v2, v80, v80
	v_max_f32_e32 v0, v2, v0
	v_max3_f32 v0, v0, v82, v83
	v_max3_f32 v0, v0, v84, v85
	v_max3_f32 v0, v0, v86, v87
	v_max3_f32 v0, v0, v88, v89
	v_max3_f32 v0, v0, v90, v91
	v_max3_f32 v0, v0, v92, v93
	v_max3_f32 v0, v0, v94, v95
	ds_bpermute_b32 v2, v209, v0
	s_waitcnt lgkmcnt(0)
	v_max_f32_e32 v2, v2, v2
	v_max_f32_e32 v0, v0, v2
	v_mul_f32_e32 v0, 0x3dd53b94, v0
	v_cmp_gt_f32_e32 vcc, v0, v198
	s_cbranch_vccz .LBB0_684
	v_max_f32_e32 v0, v0, v0
	v_max_f32_e32 v2, v198, v198
	v_max_f32_e32 v2, v2, v0
	v_sub_f32_e32 v0, v198, v2
	v_exp_f32_e32 v0, v0
	v_mov_b32_e32 v198, v2
	v_pk_mul_f32 v[78:79], v[78:79], v[0:1] op_sel_hi:[1,0]
	v_pk_mul_f32 v[76:77], v[76:77], v[0:1] op_sel_hi:[1,0]
	v_pk_mul_f32 v[74:75], v[74:75], v[0:1] op_sel_hi:[1,0]
	v_pk_mul_f32 v[72:73], v[72:73], v[0:1] op_sel_hi:[1,0]
	v_pk_mul_f32 v[70:71], v[70:71], v[0:1] op_sel_hi:[1,0]
	v_pk_mul_f32 v[68:69], v[68:69], v[0:1] op_sel_hi:[1,0]
	v_pk_mul_f32 v[66:67], v[66:67], v[0:1] op_sel_hi:[1,0]
	v_pk_mul_f32 v[64:65], v[64:65], v[0:1] op_sel_hi:[1,0]
	v_pk_mul_f32 v[62:63], v[62:63], v[0:1] op_sel_hi:[1,0]
	v_pk_mul_f32 v[60:61], v[60:61], v[0:1] op_sel_hi:[1,0]
	v_pk_mul_f32 v[58:59], v[58:59], v[0:1] op_sel_hi:[1,0]
	v_pk_mul_f32 v[56:57], v[56:57], v[0:1] op_sel_hi:[1,0]
	v_pk_mul_f32 v[54:55], v[54:55], v[0:1] op_sel_hi:[1,0]
	v_pk_mul_f32 v[52:53], v[52:53], v[0:1] op_sel_hi:[1,0]
	v_pk_mul_f32 v[50:51], v[50:51], v[0:1] op_sel_hi:[1,0]
	v_pk_mul_f32 v[48:49], v[48:49], v[0:1] op_sel_hi:[1,0]
	v_pk_mul_f32 v[46:47], v[46:47], v[0:1] op_sel_hi:[1,0]
	v_pk_mul_f32 v[44:45], v[44:45], v[0:1] op_sel_hi:[1,0]
	v_pk_mul_f32 v[42:43], v[42:43], v[0:1] op_sel_hi:[1,0]
	v_pk_mul_f32 v[40:41], v[40:41], v[0:1] op_sel_hi:[1,0]
	v_pk_mul_f32 v[38:39], v[38:39], v[0:1] op_sel_hi:[1,0]
	v_pk_mul_f32 v[36:37], v[36:37], v[0:1] op_sel_hi:[1,0]
	v_pk_mul_f32 v[34:35], v[34:35], v[0:1] op_sel_hi:[1,0]
	v_pk_mul_f32 v[32:33], v[32:33], v[0:1] op_sel_hi:[1,0]
	v_pk_mul_f32 v[30:31], v[30:31], v[0:1] op_sel_hi:[1,0]
	v_pk_mul_f32 v[28:29], v[28:29], v[0:1] op_sel_hi:[1,0]
	v_pk_mul_f32 v[26:27], v[26:27], v[0:1] op_sel_hi:[1,0]
	v_pk_mul_f32 v[24:25], v[24:25], v[0:1] op_sel_hi:[1,0]
	v_pk_mul_f32 v[22:23], v[22:23], v[0:1] op_sel_hi:[1,0]
	v_pk_mul_f32 v[20:21], v[20:21], v[0:1] op_sel_hi:[1,0]
	v_pk_mul_f32 v[18:19], v[18:19], v[0:1] op_sel_hi:[1,0]
	v_pk_mul_f32 v[16:17], v[16:17], v[0:1] op_sel_hi:[1,0]
	v_mul_f32_e32 v193, v193, v0
	s_branch .LBB0_684

	.amdhsa_kernel _Z4mega5KArgs
		.amdhsa_group_segment_fixed_size 0
		.amdhsa_private_segment_fixed_size 0
		.amdhsa_kernarg_size 592
		.amdhsa_user_sgpr_count 2
		.amdhsa_user_sgpr_dispatch_ptr 0
		.amdhsa_user_sgpr_queue_ptr 0
		.amdhsa_user_sgpr_kernarg_segment_ptr 1
		.amdhsa_user_sgpr_dispatch_id 0
		.amdhsa_user_sgpr_kernarg_preload_length 0
		.amdhsa_user_sgpr_kernarg_preload_offset 0
		.amdhsa_user_sgpr_private_segment_size 0
		.amdhsa_uses_dynamic_stack 0
		.amdhsa_enable_private_segment 0
		.amdhsa_system_sgpr_workgroup_id_x 1
		.amdhsa_system_sgpr_workgroup_id_y 0
		.amdhsa_system_sgpr_workgroup_id_z 0
		.amdhsa_system_sgpr_workgroup_info 0
		.amdhsa_system_vgpr_workitem_id 2
		.amdhsa_next_free_vgpr 256
		.amdhsa_next_free_sgpr 100
		.amdhsa_accum_offset 256
		.amdhsa_reserve_vcc 1
		.amdhsa_float_round_mode_32 0
		.amdhsa_float_round_mode_16_64 0
		.amdhsa_float_denorm_mode_32 3
		.amdhsa_float_denorm_mode_16_64 3
		.amdhsa_dx10_clamp 1
		.amdhsa_ieee_mode 1
		.amdhsa_fp16_overflow 0
		.amdhsa_tg_split 0
		.amdhsa_exception_fp_ieee_invalid_op 0
		.amdhsa_exception_fp_denorm_src 0
		.amdhsa_exception_fp_ieee_div_zero 0
		.amdhsa_exception_fp_ieee_overflow 0
		.amdhsa_exception_fp_ieee_underflow 0
		.amdhsa_exception_fp_ieee_inexact 0
		.amdhsa_exception_int_div_zero 0
	.end_amdhsa_kernel

amdhsa.kernels:
  - .agpr_count:     0
    .args:
      - .offset:         0
        .size:           336
        .value_kind:     by_value
      - .offset:         336
        .size:           4
        .value_kind:     hidden_block_count_x
      - .offset:         340
        .size:           4
        .value_kind:     hidden_block_count_y
      - .offset:         344
        .size:           4
        .value_kind:     hidden_block_count_z
      - .offset:         348
        .size:           2
        .value_kind:     hidden_group_size_x
      - .offset:         350
        .size:           2
        .value_kind:     hidden_group_size_y
      - .offset:         352
        .size:           2
        .value_kind:     hidden_group_size_z
      - .offset:         354
        .size:           2
        .value_kind:     hidden_remainder_x
      - .offset:         356
        .size:           2
        .value_kind:     hidden_remainder_y
      - .offset:         358
        .size:           2
        .value_kind:     hidden_remainder_z
      - .offset:         376
        .size:           8
        .value_kind:     hidden_global_offset_x
      - .offset:         384
        .size:           8
        .value_kind:     hidden_global_offset_y
      - .offset:         392
        .size:           8
        .value_kind:     hidden_global_offset_z
      - .offset:         400
        .size:           2
        .value_kind:     hidden_grid_dims
      - .offset:         424
        .size:           8
        .value_kind:     hidden_multigrid_sync_arg
      - .offset:         456
        .size:           4
        .value_kind:     hidden_dynamic_lds_size
    .group_segment_fixed_size: 0
    .kernarg_segment_align: 8
    .kernarg_segment_size: 592
    .language:       OpenCL C
    .language_version:
      - 2
      - 0
    .max_flat_workgroup_size: 256
    .name:           _Z4mega5KArgs
    .private_segment_fixed_size: 0
    .sgpr_count:     106
    .sgpr_spill_count: 2
    .symbol:         _Z4mega5KArgs.kd
    .uniform_work_group_size: 1
    .uses_dynamic_stack: false
    .vgpr_count:     256
    .vgpr_spill_count: 0
    .wavefront_size: 64
